# sample attention task QK^T: 32 key-cache loads issued in bulk (24 + 8) with counted waits instead of one vmcnt(0) round trip per MFMA; nt
# speedup vs baseline: 1.0034x; 1.0034x over previous
.LBB0_731:
	s_andn2_b64 vcc, exec, s[12:13]
	s_cbranch_vccnz .LBB0_722
	s_add_i32 s13, s14, s33
	s_and_b32 s14, s13, 3
	s_ashr_i32 s12, s13, 2
	s_and_b32 s13, s13, -4
	s_add_i32 s94, s13, 0x2000
	v_or_b32_e32 v96, s94, v125
	v_ashrrev_i32_e32 v97, 31, v96
	v_readlane_b32 s24, v254, 54
	v_lshl_or_b32 v103, s14, 3, v156
	v_lshlrev_b64 v[100:101], 12, v[96:97]
	v_readlane_b32 s25, v254, 55
	v_lshlrev_b32_e32 v130, 7, v103
	v_mov_b32_e32 v93, v131
	v_lshl_add_u64 v[0:1], s[24:25], 0, v[100:101]
	v_lshl_add_u64 v[0:1], v[0:1], 0, v[130:131]
	v_lshl_add_u64 v[0:1], v[0:1], 0, v[92:93]
	s_lshl_b32 s24, s14, 8
	s_mov_b32 s25, s92
	v_or_b32_e32 v182, s94, v136
	global_load_dwordx4 v[64:67], v[0:1], off
	global_load_dwordx4 v[88:91], v[0:1], off offset:32
	global_load_dwordx4 v[84:87], v[0:1], off offset:64
	global_load_dwordx4 v[80:83], v[0:1], off offset:96
	v_lshl_add_u64 v[152:153], v[140:141], 0, s[24:25]
	v_ashrrev_i32_e32 v183, 31, v182
	v_readlane_b32 s24, v254, 56
	s_lshl_b32 s13, s12, 7
	v_lshlrev_b64 v[182:183], 9, v[182:183]
	v_readlane_b32 s25, v254, 57
	v_or_b32_e32 v208, s13, v136
	v_ashrrev_i32_e32 v209, 31, v208
	v_lshl_add_u64 v[182:183], s[24:25], 0, v[182:183]
	s_lshl_b32 s24, s14, 7
	s_mov_b32 s25, s92
	v_lshl_add_u64 v[182:183], v[182:183], 0, s[24:25]
	v_lshl_add_u64 v[98:99], v[182:183], 0, v[92:93]
	v_lshlrev_b64 v[208:209], 10, v[208:209]
	s_mov_b64 s[60:61], 0x8000
	v_lshl_add_u64 v[182:183], v[152:153], 0, v[208:209]
	v_lshl_add_u64 v[208:209], v[182:183], 0, s[60:61]
	v_lshl_add_u64 v[222:223], v[208:209], 0, s[60:61]
	v_lshl_add_u64 v[252:253], v[222:223], 0, s[60:61]
	global_load_dwordx4 v[104:107], v[182:183], off nt
	global_load_dwordx4 v[108:111], v[182:183], off offset:16 nt
	global_load_dwordx4 v[112:115], v[182:183], off offset:64 nt
	global_load_dwordx4 v[116:119], v[182:183], off offset:80 nt
	global_load_dwordx4 v[120:123], v[182:183], off offset:128 nt
	global_load_dwordx4 v[144:147], v[182:183], off offset:144 nt
	global_load_dwordx4 v[148:151], v[182:183], off offset:192 nt
	global_load_dwordx4 v[184:187], v[182:183], off offset:208 nt
	global_load_dwordx4 v[188:191], v[208:209], off nt
	global_load_dwordx4 v[192:195], v[208:209], off offset:16 nt
	global_load_dwordx4 v[196:199], v[208:209], off offset:64 nt
	global_load_dwordx4 v[200:203], v[208:209], off offset:80 nt
	global_load_dwordx4 v[204:207], v[208:209], off offset:128 nt
	global_load_dwordx4 v[224:227], v[208:209], off offset:144 nt
	global_load_dwordx4 v[228:231], v[208:209], off offset:192 nt
	global_load_dwordx4 v[232:235], v[208:209], off offset:208 nt
	global_load_dwordx4 v[236:239], v[222:223], off nt
	global_load_dwordx4 v[240:243], v[222:223], off offset:16 nt
	global_load_dwordx4 v[244:247], v[222:223], off offset:64 nt
	global_load_dwordx4 v[248:251], v[222:223], off offset:80 nt
	global_load_dwordx4 v[0:3], v[222:223], off offset:128 nt
	global_load_dwordx4 v[4:7], v[222:223], off offset:144 nt
	global_load_dwordx4 v[8:11], v[222:223], off offset:192 nt
	global_load_dwordx4 v[12:15], v[222:223], off offset:208 nt
	v_mov_b32_e32 v92, 0
	s_waitcnt vmcnt(16)
	v_cvt_pk_bf16_f32 v104, v104, v105
	v_cvt_pk_bf16_f32 v105, v106, v107
	v_cvt_pk_bf16_f32 v106, v108, v109
	v_cvt_pk_bf16_f32 v107, v110, v111
	v_cvt_pk_bf16_f32 v112, v112, v113
	v_cvt_pk_bf16_f32 v113, v114, v115
	v_cvt_pk_bf16_f32 v114, v116, v117
	v_cvt_pk_bf16_f32 v115, v118, v119
	v_cvt_pk_bf16_f32 v120, v120, v121
	v_cvt_pk_bf16_f32 v121, v122, v123
	v_cvt_pk_bf16_f32 v122, v144, v145
	v_cvt_pk_bf16_f32 v123, v146, v147
	v_cvt_pk_bf16_f32 v148, v148, v149
	v_cvt_pk_bf16_f32 v149, v150, v151
	v_cvt_pk_bf16_f32 v150, v184, v185
	v_cvt_pk_bf16_f32 v151, v186, v187
	s_nop 1
	v_mfma_f32_32x32x16_bf16 v[16:31], v[104:107], v[64:67], 0
	v_mfma_f32_32x32x16_bf16 v[16:31], v[112:115], v[88:91], v[16:31]
	v_mfma_f32_32x32x16_bf16 v[16:31], v[120:123], v[84:87], v[16:31]
	v_mfma_f32_32x32x16_bf16 v[16:31], v[148:151], v[80:83], v[16:31]
	global_load_dwordx4 v[104:107], v[252:253], off nt
	global_load_dwordx4 v[108:111], v[252:253], off offset:16 nt
	global_load_dwordx4 v[112:115], v[252:253], off offset:64 nt
	global_load_dwordx4 v[116:119], v[252:253], off offset:80 nt
	global_load_dwordx4 v[120:123], v[252:253], off offset:128 nt
	global_load_dwordx4 v[144:147], v[252:253], off offset:144 nt
	global_load_dwordx4 v[148:151], v[252:253], off offset:192 nt
	global_load_dwordx4 v[184:187], v[252:253], off offset:208 nt
	s_waitcnt vmcnt(16)
	v_cvt_pk_bf16_f32 v188, v188, v189
	v_cvt_pk_bf16_f32 v189, v190, v191
	v_cvt_pk_bf16_f32 v190, v192, v193
	v_cvt_pk_bf16_f32 v191, v194, v195
	v_cvt_pk_bf16_f32 v196, v196, v197
	v_cvt_pk_bf16_f32 v197, v198, v199
	v_cvt_pk_bf16_f32 v198, v200, v201
	v_cvt_pk_bf16_f32 v199, v202, v203
	v_cvt_pk_bf16_f32 v204, v204, v205
	v_cvt_pk_bf16_f32 v205, v206, v207
	v_cvt_pk_bf16_f32 v206, v224, v225
	v_cvt_pk_bf16_f32 v207, v226, v227
	v_cvt_pk_bf16_f32 v228, v228, v229
	v_cvt_pk_bf16_f32 v229, v230, v231
	v_cvt_pk_bf16_f32 v230, v232, v233
	v_cvt_pk_bf16_f32 v231, v234, v235
	s_nop 1
	v_mfma_f32_32x32x16_bf16 v[32:47], v[188:191], v[64:67], 0
	v_mfma_f32_32x32x16_bf16 v[32:47], v[196:199], v[88:91], v[32:47]
	v_mfma_f32_32x32x16_bf16 v[32:47], v[204:207], v[84:87], v[32:47]
	v_mfma_f32_32x32x16_bf16 v[32:47], v[228:231], v[80:83], v[32:47]
	v_mov_b32_e32 v188, 0
	v_mov_b32_e32 v189, 0
	v_mov_b32_e32 v190, 0
	v_mov_b32_e32 v191, 0
	v_mov_b32_e32 v192, 0
	v_mov_b32_e32 v193, 0
	v_mov_b32_e32 v194, 0
	v_mov_b32_e32 v195, 0
	v_mov_b32_e32 v196, 0
	v_mov_b32_e32 v197, 0
	v_mov_b32_e32 v198, 0
	v_mov_b32_e32 v199, 0
	v_mov_b32_e32 v200, 0
	v_mov_b32_e32 v201, 0
	v_mov_b32_e32 v202, 0
	v_mov_b32_e32 v203, 0
	s_and_saveexec_b64 vcc, s[42:43]
	global_load_dwordx4 v[188:191], v[98:99], off
	global_load_dwordx4 v[192:195], v[98:99], off offset:32
	global_load_dwordx4 v[196:199], v[98:99], off offset:64
	global_load_dwordx4 v[200:203], v[98:99], off offset:96
	s_or_b64 exec, exec, vcc
	s_waitcnt vmcnt(12)
	v_cvt_pk_bf16_f32 v236, v236, v237
	v_cvt_pk_bf16_f32 v237, v238, v239
	v_cvt_pk_bf16_f32 v238, v240, v241
	v_cvt_pk_bf16_f32 v239, v242, v243
	v_cvt_pk_bf16_f32 v244, v244, v245
	v_cvt_pk_bf16_f32 v245, v246, v247
	v_cvt_pk_bf16_f32 v246, v248, v249
	v_cvt_pk_bf16_f32 v247, v250, v251
	v_cvt_pk_bf16_f32 v0, v0, v1
	v_cvt_pk_bf16_f32 v1, v2, v3
	v_cvt_pk_bf16_f32 v2, v4, v5
	v_cvt_pk_bf16_f32 v3, v6, v7
	v_cvt_pk_bf16_f32 v8, v8, v9
	v_cvt_pk_bf16_f32 v9, v10, v11
	v_cvt_pk_bf16_f32 v10, v12, v13
	v_cvt_pk_bf16_f32 v11, v14, v15
	s_nop 1
	v_mfma_f32_32x32x16_bf16 v[48:63], v[236:239], v[64:67], 0
	v_mfma_f32_32x32x16_bf16 v[48:63], v[244:247], v[88:91], v[48:63]
	v_mfma_f32_32x32x16_bf16 v[48:63], v[0:3], v[84:87], v[48:63]
	v_mfma_f32_32x32x16_bf16 v[48:63], v[8:11], v[80:83], v[48:63]
	s_waitcnt vmcnt(4)
	v_cvt_pk_bf16_f32 v104, v104, v105
	v_cvt_pk_bf16_f32 v105, v106, v107
	v_cvt_pk_bf16_f32 v106, v108, v109
	v_cvt_pk_bf16_f32 v107, v110, v111
	v_cvt_pk_bf16_f32 v112, v112, v113
	v_cvt_pk_bf16_f32 v113, v114, v115
	v_cvt_pk_bf16_f32 v114, v116, v117
	v_cvt_pk_bf16_f32 v115, v118, v119
	v_cvt_pk_bf16_f32 v120, v120, v121
	v_cvt_pk_bf16_f32 v121, v122, v123
	v_cvt_pk_bf16_f32 v122, v144, v145
	v_cvt_pk_bf16_f32 v123, v146, v147
	v_cvt_pk_bf16_f32 v148, v148, v149
	v_cvt_pk_bf16_f32 v149, v150, v151
	v_cvt_pk_bf16_f32 v150, v184, v185
	v_cvt_pk_bf16_f32 v151, v186, v187
	s_nop 1
	v_mfma_f32_32x32x16_bf16 v[0:15], v[104:107], v[64:67], 0
	v_mfma_f32_32x32x16_bf16 v[0:15], v[112:115], v[88:91], v[0:15]
	v_mfma_f32_32x32x16_bf16 v[0:15], v[120:123], v[84:87], v[0:15]
	v_mfma_f32_32x32x16_bf16 v[0:15], v[148:151], v[80:83], v[0:15]
	s_lshl_b32 s14, s14, 6
	v_readlane_b32 s56, v254, 22
	v_readlane_b32 s58, v254, 24
	v_readlane_b32 s59, v254, 25
	s_waitcnt vmcnt(0)
	v_mfma_f32_32x32x16_bf16 v[64:79], v[188:191], v[64:67], 0
	v_mfma_f32_32x32x16_bf16 v[64:79], v[192:195], v[88:91], v[64:79]
	v_mfma_f32_32x32x16_bf16 v[64:79], v[196:199], v[84:87], v[64:79]
	v_lshlrev_b32_e32 v84, 2, v103
	v_mfma_f32_32x32x16_bf16 v[64:79], v[200:203], v[80:83], v[64:79]


	v_cndmask_b32_e64 v18, v179, v18, s[48:49]
	v_cndmask_b32_e64 v19, v19, v179, s[50:51]
	v_readlane_b32 s57, v254, 23
	v_readlane_b32 s60, v254, 26
	global_load_dword v84, v84, s[58:59] nt
	s_nop 6
	v_cndmask_b32_e64 v69, v179, v16, s[44:45]
	v_cndmask_b32_e64 v70, v17, v179, s[46:47]
	v_and_b32_e32 v17, 64, v102
	v_xor_b32_e32 v16, 32, v102
	v_max_f32_e32 v68, v69, v69
	v_add_u32_e32 v17, 64, v17
	v_max_f32_e32 v68, 0xf149f2ca, v68
	v_cmp_lt_i32_e32 vcc, v16, v17
	v_max3_f32 v17, v68, v70, v18
	v_cndmask_b32_e64 v77, v66, v179, s[48:49]
	v_cndmask_b32_e32 v16, v102, v16, vcc
	v_lshlrev_b32_e32 v68, 2, v16
	v_max3_f32 v16, v17, v19, v20
	v_max3_f32 v16, v16, v21, v22
	v_max3_f32 v16, v16, v23, v24
	v_max3_f32 v16, v16, v25, v26
	v_max3_f32 v71, v16, v27, v28
	v_cndmask_b32_e64 v17, v64, v179, s[44:45]
	v_max3_f32 v64, v71, v29, v30
	v_max3_f32 v64, v64, v31, v32
	v_max3_f32 v64, v64, v33, v34
	v_max3_f32 v64, v64, v35, v36
	v_max3_f32 v64, v64, v37, v38
	v_max3_f32 v64, v64, v39, v40
	v_max3_f32 v64, v64, v41, v42
	v_max3_f32 v64, v64, v43, v44
	v_max3_f32 v64, v64, v45, v46
	v_max3_f32 v64, v64, v47, v48
	v_max3_f32 v64, v64, v49, v50
	v_max3_f32 v64, v64, v51, v52
	v_max3_f32 v64, v64, v53, v54
	v_max3_f32 v64, v64, v55, v56
	v_max3_f32 v64, v64, v57, v58
	v_max3_f32 v64, v64, v59, v60
	v_max3_f32 v64, v64, v61, v62
	v_max3_f32 v64, v64, v63, v0
	v_max3_f32 v64, v64, v1, v2
	v_max3_f32 v64, v64, v3, v4
	v_max3_f32 v64, v64, v5, v6
	v_max3_f32 v64, v64, v7, v8
	v_max3_f32 v64, v64, v9, v10
	v_max3_f32 v64, v64, v11, v12
	v_max3_f32 v64, v64, v13, v14
	v_cndmask_b32_e64 v16, v179, v65, s[46:47]
	v_max3_f32 v64, v64, v15, v17
	v_cndmask_b32_e64 v76, v179, v67, s[50:51]
	v_max3_f32 v64, v64, v16, v77
	v_max3_f32 v64, v64, v76, s17
	ds_bpermute_b32 v65, v68, v64
	v_readlane_b32 s61, v254, 27
	v_readlane_b32 s62, v254, 28
	v_readlane_b32 s63, v254, 29
	v_readlane_b32 s64, v254, 30
	s_waitcnt lgkmcnt(0)
	v_max_f32_e32 v65, v65, v65
	v_max_f32_e32 v64, v64, v65
	v_mul_f32_e32 v64, 0x3e38aa3b, v64
	v_readlane_b32 s65, v254, 31
	v_readlane_b32 s66, v254, 32
	v_readlane_b32 s67, v254, 33
	v_readlane_b32 s68, v254, 34
	v_readlane_b32 s69, v254, 35
	v_readlane_b32 s70, v254, 36
	v_readlane_b32 s71, v254, 37
	v_readlane_b32 s56, v254, 6
	v_readlane_b32 s62, v254, 12
	v_readlane_b32 s63, v254, 13
	v_lshlrev_b32_e32 v130, 2, v136
	v_readlane_b32 s57, v254, 7
	v_readlane_b32 s56, v254, 58
	v_readlane_b32 s57, v254, 59
	v_readlane_b32 s58, v254, 8
	v_readlane_b32 s59, v254, 9
	v_readlane_b32 s60, v254, 10
	v_readlane_b32 s61, v254, 11
	v_readlane_b32 s64, v254, 14
	v_readlane_b32 s65, v254, 15
	v_readlane_b32 s66, v254, 16
	v_readlane_b32 s67, v254, 17
	v_readlane_b32 s68, v254, 18
	s_waitcnt vmcnt(0)
	v_mul_f32_e32 v155, 0x3fb8aa3b, v84
	v_max_f32_e32 v181, v64, v155
	v_fma_f32 v64, v69, s18, -v181
	v_fma_f32 v65, v70, s18, -v181
	v_fma_f32 v66, v18, s18, -v181
	v_exp_f32_e32 v18, v64
	v_fma_f32 v67, v19, s18, -v181
	v_exp_f32_e32 v19, v65
	v_fma_f32 v69, v20, s18, -v181
	v_exp_f32_e32 v20, v66
	v_fma_f32 v70, v21, s18, -v181
	v_fma_f32 v26, v26, s18, -v181
	v_exp_f32_e32 v21, v67
	v_fma_f32 v71, v22, s18, -v181
	v_exp_f32_e32 v22, v69
	v_exp_f32_e32 v80, v26
	v_add_f32_e32 v26, 0, v18
	v_fma_f32 v72, v23, s18, -v181
	v_exp_f32_e32 v23, v70
	v_add_f32_e32 v26, v19, v26
	v_fma_f32 v73, v24, s18, -v181
	v_exp_f32_e32 v24, v71
	v_add_f32_e32 v26, v20, v26
	v_fma_f32 v74, v25, s18, -v181
	v_exp_f32_e32 v25, v72
	v_add_f32_e32 v26, v21, v26
	v_exp_f32_e32 v78, v73
	v_add_f32_e32 v26, v22, v26
	v_exp_f32_e32 v79, v74
	v_add_f32_e32 v26, v23, v26
	v_fma_f32 v27, v27, s18, -v181
	v_add_f32_e32 v26, v24, v26
	v_fma_f32 v28, v28, s18, -v181
	v_exp_f32_e32 v81, v27
	v_add_f32_e32 v26, v25, v26
	v_fma_f32 v29, v29, s18, -v181
	v_exp_f32_e32 v82, v28
	v_add_f32_e32 v26, v78, v26
	v_fma_f32 v30, v30, s18, -v181
	v_exp_f32_e32 v83, v29
	v_add_f32_e32 v26, v79, v26
	v_add_f32_e32 v26, v80, v26
	v_exp_f32_e32 v86, v30
	v_fma_f32 v27, v31, s18, -v181
	v_add_f32_e32 v26, v81, v26
	v_exp_f32_e32 v88, v27
	v_fma_f32 v27, v32, s18, -v181
	v_add_f32_e32 v26, v82, v26
	v_exp_f32_e32 v32, v27
	v_fma_f32 v27, v33, s18, -v181
	v_add_f32_e32 v26, v83, v26
	v_exp_f32_e32 v84, v27
	v_fma_f32 v27, v34, s18, -v181
	v_add_f32_e32 v26, v86, v26
	v_exp_f32_e32 v85, v27
	v_fma_f32 v27, v35, s18, -v181
	v_add_f32_e32 v26, v88, v26
	v_exp_f32_e32 v87, v27
	v_fma_f32 v27, v36, s18, -v181
	v_add_f32_e32 v26, v32, v26
	v_exp_f32_e32 v36, v27
	v_fma_f32 v27, v37, s18, -v181
	v_add_f32_e32 v26, v84, v26
	v_exp_f32_e32 v89, v27
	v_fma_f32 v27, v38, s18, -v181
	v_add_f32_e32 v26, v85, v26
	v_exp_f32_e32 v38, v27
	v_fma_f32 v27, v39, s18, -v181
	v_add_f32_e32 v26, v87, v26
	v_exp_f32_e32 v90, v27
	v_fma_f32 v27, v40, s18, -v181
	v_add_f32_e32 v26, v36, v26
	v_exp_f32_e32 v37, v27
	v_fma_f32 v27, v41, s18, -v181
	v_add_f32_e32 v26, v89, v26
	v_exp_f32_e32 v39, v27
	v_fma_f32 v27, v42, s18, -v181
	v_add_f32_e32 v26, v38, v26
	v_exp_f32_e32 v33, v27
	v_fma_f32 v27, v43, s18, -v181
	v_add_f32_e32 v26, v90, v26
	v_exp_f32_e32 v64, v27
	v_fma_f32 v27, v44, s18, -v181
	v_add_f32_e32 v26, v37, v26
	v_exp_f32_e32 v65, v27
	v_fma_f32 v27, v45, s18, -v181
	v_add_f32_e32 v26, v39, v26
	v_exp_f32_e32 v66, v27
	v_fma_f32 v27, v46, s18, -v181
	v_add_f32_e32 v26, v33, v26
	v_exp_f32_e32 v67, v27
	v_fma_f32 v27, v47, s18, -v181
	v_add_f32_e32 v26, v64, v26
	v_exp_f32_e32 v69, v27
	v_fma_f32 v27, v48, s18, -v181
	v_add_f32_e32 v26, v65, v26
	v_exp_f32_e32 v44, v27
	v_fma_f32 v27, v49, s18, -v181
	v_add_f32_e32 v26, v66, v26
	v_exp_f32_e32 v45, v27
	v_fma_f32 v27, v50, s18, -v181
	v_add_f32_e32 v26, v67, v26
	v_exp_f32_e32 v46, v27
	v_fma_f32 v27, v51, s18, -v181
	v_add_f32_e32 v26, v69, v26
	v_exp_f32_e32 v47, v27
	v_fma_f32 v27, v52, s18, -v181
	v_add_f32_e32 v26, v44, v26
	v_exp_f32_e32 v49, v27
	v_fma_f32 v27, v53, s18, -v181
	v_add_f32_e32 v26, v45, v26
	v_exp_f32_e32 v51, v27
	v_fma_f32 v27, v54, s18, -v181
	v_add_f32_e32 v26, v46, v26
	v_exp_f32_e32 v53, v27
	v_fma_f32 v27, v55, s18, -v181
	v_add_f32_e32 v26, v47, v26
	v_exp_f32_e32 v55, v27
	v_fma_f32 v27, v56, s18, -v181
	v_add_f32_e32 v26, v49, v26
	v_exp_f32_e32 v48, v27
	v_fma_f32 v27, v57, s18, -v181
	v_add_f32_e32 v26, v51, v26
	v_exp_f32_e32 v50, v27
	v_fma_f32 v27, v58, s18, -v181
	v_add_f32_e32 v26, v53, v26
	v_exp_f32_e32 v52, v27
	v_fma_f32 v27, v59, s18, -v181
	v_add_f32_e32 v26, v55, v26
	v_exp_f32_e32 v54, v27
	v_fma_f32 v27, v60, s18, -v181
	v_add_f32_e32 v26, v48, v26
	v_exp_f32_e32 v57, v27
	v_fma_f32 v27, v61, s18, -v181
	v_add_f32_e32 v26, v50, v26
	v_exp_f32_e32 v59, v27
	v_fma_f32 v27, v62, s18, -v181
	v_add_f32_e32 v26, v52, v26
	v_exp_f32_e32 v61, v27
	v_fma_f32 v27, v63, s18, -v181
	v_add_f32_e32 v26, v54, v26
	v_exp_f32_e32 v70, v27
	v_fma_f32 v0, v0, s18, -v181
	v_add_f32_e32 v26, v57, v26
	v_exp_f32_e32 v56, v0
	v_fma_f32 v1, v1, s18, -v181
	v_add_f32_e32 v0, v59, v26
	v_exp_f32_e32 v58, v1
	v_fma_f32 v1, v2, s18, -v181
	v_add_f32_e32 v0, v61, v0
	v_exp_f32_e32 v60, v1
	v_fma_f32 v1, v3, s18, -v181
	v_add_f32_e32 v0, v70, v0
	v_exp_f32_e32 v63, v1
	v_fma_f32 v1, v4, s18, -v181
	v_add_f32_e32 v0, v56, v0
	v_exp_f32_e32 v71, v1
	v_fma_f32 v1, v5, s18, -v181
	v_add_f32_e32 v0, v58, v0
	v_exp_f32_e32 v73, v1
	v_fma_f32 v1, v6, s18, -v181
	v_add_f32_e32 v0, v60, v0
	v_exp_f32_e32 v74, v1
	v_fma_f32 v1, v7, s18, -v181
	v_add_f32_e32 v0, v63, v0
	v_exp_f32_e32 v75, v1
	v_fma_f32 v1, v8, s18, -v181
	v_add_f32_e32 v0, v71, v0
	v_exp_f32_e32 v62, v1
	v_add_f32_e32 v0, v73, v0
	v_add_f32_e32 v0, v74, v0
	v_or_b32_e32 v34, s13, v137
	s_lshl_b32 s13, s14, 2
	v_add_f32_e32 v0, v75, v0
	s_add_u32 vcc_lo, s62, s13
	v_add_f32_e32 v91, v62, v0
	v_fma_f32 v0, v9, s18, -v181
	s_addc_u32 vcc_hi, s63, 0
	v_ashrrev_i32_e32 v35, 31, v34
	v_or_b32_e32 v4, 1, v34
	v_or_b32_e32 v8, 2, v34
	v_or_b32_e32 v28, 3, v34
	v_or_b32_e32 v42, 8, v34
	v_or_b32_e32 v94, 9, v34
	v_or_b32_e32 v104, 10, v34
	v_or_b32_e32 v108, 11, v34
	v_exp_f32_e32 v72, v0
	v_lshl_add_u64 v[40:41], vcc, 0, v[130:131]
	v_lshlrev_b64 v[0:1], 10, v[34:35]
	v_ashrrev_i32_e32 v5, 31, v4
	v_ashrrev_i32_e32 v9, 31, v8
	v_ashrrev_i32_e32 v29, 31, v28
	v_ashrrev_i32_e32 v43, 31, v42
	v_ashrrev_i32_e32 v95, 31, v94
	v_ashrrev_i32_e32 v105, 31, v104
	v_ashrrev_i32_e32 v109, 31, v108
	v_lshl_add_u64 v[2:3], v[40:41], 0, v[0:1]
	v_lshlrev_b64 v[4:5], 10, v[4:5]
	v_lshlrev_b64 v[8:9], 10, v[8:9]
	v_lshlrev_b64 v[28:29], 10, v[28:29]
	v_lshlrev_b64 v[92:93], 10, v[42:43]
	v_lshlrev_b64 v[94:95], 10, v[94:95]
	v_lshlrev_b64 v[104:105], 10, v[104:105]
	v_lshlrev_b64 v[108:109], 10, v[108:109]
	v_lshl_add_u64 v[6:7], v[40:41], 0, v[4:5]
	v_lshl_add_u64 v[26:27], v[40:41], 0, v[8:9]
	v_lshl_add_u64 v[30:31], v[40:41], 0, v[28:29]
	v_lshl_add_u64 v[42:43], v[40:41], 0, v[92:93]
	v_lshl_add_u64 v[98:99], v[40:41], 0, v[94:95]
	v_lshl_add_u64 v[106:107], v[40:41], 0, v[104:105]
	v_lshl_add_u64 v[110:111], v[40:41], 0, v[108:109]
	global_load_dword v35, v[2:3], off nt
	global_load_dword v143, v[6:7], off nt
	global_load_dword v144, v[26:27], off nt
	global_load_dword v145, v[30:31], off nt
	global_load_dword v146, v[42:43], off nt
	global_load_dword v147, v[98:99], off nt
	global_load_dword v148, v[106:107], off nt
	global_load_dword v149, v[110:111], off nt
	v_lshlrev_b32_e32 v130, 2, v124
	v_lshl_add_u64 v[42:43], vcc, 0, v[130:131]
	v_lshl_add_u64 v[0:1], v[42:43], 0, v[0:1]
	v_lshl_add_u64 v[2:3], v[42:43], 0, v[4:5]
	v_lshl_add_u64 v[4:5], v[42:43], 0, v[8:9]
	v_lshl_add_u64 v[6:7], v[42:43], 0, v[28:29]
	v_lshl_add_u64 v[8:9], v[42:43], 0, v[92:93]
	v_lshl_add_u64 v[26:27], v[42:43], 0, v[94:95]
	v_lshl_add_u64 v[28:29], v[42:43], 0, v[104:105]
	v_lshl_add_u64 v[30:31], v[42:43], 0, v[108:109]
	global_load_dword v130, v[0:1], off nt
	global_load_dword v150, v[2:3], off nt
	global_load_dword v151, v[4:5], off nt
	global_load_dword v152, v[6:7], off nt
	global_load_dword v153, v[8:9], off nt
	global_load_dword v182, v[26:27], off nt
	global_load_dword v183, v[28:29], off nt
	global_load_dword v184, v[30:31], off nt
	v_or_b32_e32 v0, 16, v34
	v_ashrrev_i32_e32 v1, 31, v0
	v_or_b32_e32 v4, 17, v34
	v_or_b32_e32 v8, 18, v34
	v_or_b32_e32 v28, 19, v34
	v_or_b32_e32 v92, 24, v34
	v_or_b32_e32 v98, 25, v34
	v_or_b32_e32 v106, 26, v34
	v_or_b32_e32 v110, 27, v34
	v_lshlrev_b64 v[0:1], 10, v[0:1]
	v_ashrrev_i32_e32 v5, 31, v4
	v_ashrrev_i32_e32 v9, 31, v8
	v_ashrrev_i32_e32 v29, 31, v28
	v_ashrrev_i32_e32 v93, 31, v92
	v_ashrrev_i32_e32 v99, 31, v98
	v_ashrrev_i32_e32 v107, 31, v106
	v_ashrrev_i32_e32 v111, 31, v110
	v_lshl_add_u64 v[2:3], v[40:41], 0, v[0:1]
	v_lshlrev_b64 v[4:5], 10, v[4:5]
	v_lshlrev_b64 v[8:9], 10, v[8:9]
	v_lshlrev_b64 v[28:29], 10, v[28:29]
	v_lshlrev_b64 v[92:93], 10, v[92:93]
	v_lshlrev_b64 v[98:99], 10, v[98:99]
	v_lshlrev_b64 v[106:107], 10, v[106:107]
	v_lshlrev_b64 v[110:111], 10, v[110:111]
	v_lshl_add_u64 v[6:7], v[40:41], 0, v[4:5]
	v_lshl_add_u64 v[26:27], v[40:41], 0, v[8:9]
	v_lshl_add_u64 v[30:31], v[40:41], 0, v[28:29]
	v_lshl_add_u64 v[94:95], v[40:41], 0, v[92:93]
	v_lshl_add_u64 v[104:105], v[40:41], 0, v[98:99]
	v_lshl_add_u64 v[108:109], v[40:41], 0, v[106:107]
	v_lshl_add_u64 v[112:113], v[40:41], 0, v[110:111]
	global_load_dword v185, v[2:3], off nt
	global_load_dword v186, v[6:7], off nt
	global_load_dword v187, v[26:27], off nt
	global_load_dword v188, v[30:31], off nt
	global_load_dword v189, v[94:95], off nt
	global_load_dword v190, v[104:105], off nt
	global_load_dword v191, v[108:109], off nt
	global_load_dword v192, v[112:113], off nt
	v_lshl_add_u64 v[0:1], v[42:43], 0, v[0:1]
	v_lshl_add_u64 v[2:3], v[42:43], 0, v[4:5]
	v_lshl_add_u64 v[4:5], v[42:43], 0, v[8:9]
	v_lshl_add_u64 v[6:7], v[42:43], 0, v[28:29]
	v_lshl_add_u64 v[8:9], v[42:43], 0, v[92:93]
	v_lshl_add_u64 v[26:27], v[42:43], 0, v[98:99]
	v_lshl_add_u64 v[28:29], v[42:43], 0, v[106:107]
	v_lshl_add_u64 v[30:31], v[42:43], 0, v[110:111]
	global_load_dword v193, v[0:1], off nt
	global_load_dword v194, v[2:3], off nt
	global_load_dword v195, v[4:5], off nt
	global_load_dword v196, v[6:7], off nt
	global_load_dword v197, v[8:9], off nt
	global_load_dword v198, v[26:27], off nt
	global_load_dword v199, v[28:29], off nt
	global_load_dword v200, v[30:31], off nt
	v_or_b32_e32 v0, 32, v34
	v_ashrrev_i32_e32 v1, 31, v0
	v_or_b32_e32 v4, 33, v34
	v_or_b32_e32 v8, 34, v34
	v_or_b32_e32 v28, 35, v34
	v_or_b32_e32 v92, 40, v34
	v_or_b32_e32 v98, 41, v34
	v_or_b32_e32 v106, 42, v34
	v_or_b32_e32 v110, 43, v34
	v_lshlrev_b64 v[0:1], 10, v[0:1]
	v_ashrrev_i32_e32 v5, 31, v4
	v_ashrrev_i32_e32 v9, 31, v8
	v_ashrrev_i32_e32 v29, 31, v28
	v_ashrrev_i32_e32 v93, 31, v92
	v_ashrrev_i32_e32 v99, 31, v98
	v_ashrrev_i32_e32 v107, 31, v106
	v_ashrrev_i32_e32 v111, 31, v110
	v_lshl_add_u64 v[2:3], v[40:41], 0, v[0:1]
	v_lshlrev_b64 v[4:5], 10, v[4:5]
	v_lshlrev_b64 v[8:9], 10, v[8:9]
	v_lshlrev_b64 v[28:29], 10, v[28:29]
	v_lshlrev_b64 v[92:93], 10, v[92:93]
	v_lshlrev_b64 v[98:99], 10, v[98:99]
	v_lshlrev_b64 v[106:107], 10, v[106:107]
	v_lshlrev_b64 v[110:111], 10, v[110:111]
	v_lshl_add_u64 v[6:7], v[40:41], 0, v[4:5]
	v_lshl_add_u64 v[26:27], v[40:41], 0, v[8:9]
	v_lshl_add_u64 v[30:31], v[40:41], 0, v[28:29]
	v_lshl_add_u64 v[94:95], v[40:41], 0, v[92:93]
	v_lshl_add_u64 v[104:105], v[40:41], 0, v[98:99]
	v_lshl_add_u64 v[108:109], v[40:41], 0, v[106:107]
	v_lshl_add_u64 v[112:113], v[40:41], 0, v[110:111]
	global_load_dword v201, v[2:3], off nt
	global_load_dword v202, v[6:7], off nt
	global_load_dword v203, v[26:27], off nt
	global_load_dword v204, v[30:31], off nt
	global_load_dword v205, v[94:95], off nt
	global_load_dword v206, v[104:105], off nt
	global_load_dword v207, v[108:109], off nt
	global_load_dword v208, v[112:113], off nt
	v_lshl_add_u64 v[0:1], v[42:43], 0, v[0:1]
	v_lshl_add_u64 v[2:3], v[42:43], 0, v[4:5]
	v_lshl_add_u64 v[4:5], v[42:43], 0, v[8:9]
	v_lshl_add_u64 v[6:7], v[42:43], 0, v[28:29]
	v_lshl_add_u64 v[8:9], v[42:43], 0, v[92:93]
	v_lshl_add_u64 v[26:27], v[42:43], 0, v[98:99]
	v_lshl_add_u64 v[28:29], v[42:43], 0, v[106:107]
	v_lshl_add_u64 v[30:31], v[42:43], 0, v[110:111]
	global_load_dword v209, v[0:1], off nt
	global_load_dword v221, v[2:3], off nt
	global_load_dword v222, v[4:5], off nt
	global_load_dword v223, v[6:7], off nt
	global_load_dword v224, v[8:9], off nt
	global_load_dword v225, v[26:27], off nt
	global_load_dword v226, v[28:29], off nt
	global_load_dword v227, v[30:31], off nt
	v_or_b32_e32 v0, 48, v34
	v_ashrrev_i32_e32 v1, 31, v0
	v_or_b32_e32 v2, 49, v34
	v_or_b32_e32 v4, 50, v34
	v_or_b32_e32 v6, 51, v34
	v_or_b32_e32 v8, 56, v34
	v_or_b32_e32 v26, 57, v34
	v_or_b32_e32 v28, 58, v34
	v_or_b32_e32 v30, 59, v34
	v_lshlrev_b64 v[108:109], 10, v[0:1]
	v_ashrrev_i32_e32 v3, 31, v2
	v_ashrrev_i32_e32 v5, 31, v4
	v_ashrrev_i32_e32 v7, 31, v6
	v_ashrrev_i32_e32 v9, 31, v8
	v_ashrrev_i32_e32 v27, 31, v26
	v_ashrrev_i32_e32 v29, 31, v28
	v_ashrrev_i32_e32 v31, 31, v30
	v_lshl_add_u64 v[0:1], v[40:41], 0, v[108:109]
	v_lshlrev_b64 v[110:111], 10, v[2:3]
	v_lshlrev_b64 v[112:113], 10, v[4:5]
	v_lshlrev_b64 v[114:115], 10, v[6:7]
	v_lshlrev_b64 v[116:117], 10, v[8:9]
	v_lshlrev_b64 v[118:119], 10, v[26:27]
	v_lshlrev_b64 v[120:121], 10, v[28:29]
	v_lshlrev_b64 v[122:123], 10, v[30:31]
	v_lshl_add_u64 v[2:3], v[40:41], 0, v[110:111]
	v_lshl_add_u64 v[4:5], v[40:41], 0, v[112:113]
	v_lshl_add_u64 v[6:7], v[40:41], 0, v[114:115]
	v_lshl_add_u64 v[8:9], v[40:41], 0, v[116:117]
	v_lshl_add_u64 v[26:27], v[40:41], 0, v[118:119]
	v_lshl_add_u64 v[28:29], v[40:41], 0, v[120:121]
	v_lshl_add_u64 v[30:31], v[40:41], 0, v[122:123]
	global_load_dword v228, v[0:1], off nt
	global_load_dword v229, v[2:3], off nt
	global_load_dword v230, v[4:5], off nt
	global_load_dword v231, v[6:7], off nt
	global_load_dword v232, v[8:9], off nt
	global_load_dword v233, v[26:27], off nt
	global_load_dword v234, v[28:29], off nt
	global_load_dword v235, v[30:31], off nt
	v_fma_f32 v1, v10, s18, -v181
	v_exp_f32_e32 v93, v1
	v_fma_f32 v1, v11, s18, -v181
	v_exp_f32_e32 v94, v1
	v_fma_f32 v1, v12, s18, -v181
	v_exp_f32_e32 v95, v1
	v_fma_f32 v1, v13, s18, -v181
	v_add_f32_e32 v0, v72, v91
	v_exp_f32_e32 v98, v1
	v_add_f32_e32 v0, v93, v0
	v_add_f32_e32 v0, v94, v0
	v_add_f32_e32 v0, v95, v0
	v_add_f32_e32 v8, v98, v0
	v_fma_f32 v0, v14, s18, -v181
	v_exp_f32_e32 v99, v0
	v_fma_f32 v0, v15, s18, -v181
	v_exp_f32_e32 v102, v0
	v_fma_f32 v0, v17, s18, -v181
	v_exp_f32_e32 v91, v0
	v_fma_f32 v0, v16, s18, -v181
	v_exp_f32_e32 v92, v0
	s_waitcnt vmcnt(54)
	v_cvt_pk_bf16_f32 v0, v35, v143
	s_waitcnt vmcnt(52)
	v_cvt_pk_bf16_f32 v1, v144, v145
	s_waitcnt vmcnt(50)
	v_cvt_pk_bf16_f32 v2, v146, v147
	s_waitcnt vmcnt(48)
	v_cvt_pk_bf16_f32 v3, v148, v149
	v_cvt_pk_bf16_f32 v4, v18, v19
	v_cvt_pk_bf16_f32 v5, v20, v21
	v_cvt_pk_bf16_f32 v6, v22, v23
	v_cvt_pk_bf16_f32 v7, v24, v25
	v_add_f32_e32 v8, v99, v8
	v_add_f32_e32 v8, v102, v8
	v_mfma_f32_32x32x16_bf16 v[16:31], v[0:3], v[4:7], 0
	s_waitcnt vmcnt(46)
	v_cvt_pk_bf16_f32 v0, v130, v150
	s_waitcnt vmcnt(44)
	v_cvt_pk_bf16_f32 v1, v151, v152
	s_waitcnt vmcnt(42)
	v_cvt_pk_bf16_f32 v2, v153, v182
	s_waitcnt vmcnt(40)
	v_cvt_pk_bf16_f32 v3, v183, v184
	s_waitcnt vmcnt(38)
	v_cvt_pk_bf16_f32 v104, v185, v186
	s_waitcnt vmcnt(36)
	v_cvt_pk_bf16_f32 v105, v187, v188
	s_waitcnt vmcnt(34)
	v_cvt_pk_bf16_f32 v106, v189, v190
	s_waitcnt vmcnt(32)
	v_cvt_pk_bf16_f32 v107, v191, v192
	v_add_f32_e32 v8, v91, v8
	v_add_f32_e32 v35, v92, v8
	v_mfma_f32_32x32x16_bf16 v[0:15], v[0:3], v[4:7], 0
	v_cvt_pk_bf16_f32 v78, v78, v79
	v_cvt_pk_bf16_f32 v79, v80, v81
	v_cvt_pk_bf16_f32 v80, v82, v83
	v_cvt_pk_bf16_f32 v81, v86, v88
	v_cvt_pk_bf16_f32 v82, v32, v84
	v_cvt_pk_bf16_f32 v83, v85, v87
	v_cvt_pk_bf16_f32 v84, v36, v89
	v_mfma_f32_32x32x16_bf16 v[16:31], v[104:107], v[78:81], v[16:31]
	s_waitcnt vmcnt(30)
	v_cvt_pk_bf16_f32 v104, v193, v194
	s_waitcnt vmcnt(28)
	v_cvt_pk_bf16_f32 v105, v195, v196
	s_waitcnt vmcnt(26)
	v_cvt_pk_bf16_f32 v106, v197, v198
	s_waitcnt vmcnt(24)
	v_cvt_pk_bf16_f32 v107, v199, v200
	s_waitcnt vmcnt(14)
	v_cvt_pk_bf16_f32 v86, v209, v221
	s_waitcnt vmcnt(12)
	v_cvt_pk_bf16_f32 v87, v222, v223
	s_waitcnt vmcnt(10)
	v_cvt_pk_bf16_f32 v88, v224, v225
	v_mfma_f32_32x32x16_bf16 v[0:15], v[104:107], v[78:81], v[0:15]
	v_cvt_pk_bf16_f32 v78, v201, v202
	v_cvt_pk_bf16_f32 v79, v203, v204
	v_cvt_pk_bf16_f32 v80, v205, v206
	v_cvt_pk_bf16_f32 v81, v207, v208
	s_waitcnt vmcnt(8)
	v_cvt_pk_bf16_f32 v89, v226, v227
	v_cvt_pk_bf16_f32 v85, v38, v90
	v_lshl_add_u64 v[104:105], v[42:43], 0, v[118:119]
	v_lshl_add_u64 v[106:107], v[42:43], 0, v[120:121]
	v_mfma_f32_32x32x16_bf16 v[16:31], v[78:81], v[82:85], v[16:31]
	v_lshl_add_u64 v[80:81], v[42:43], 0, v[108:109]
	v_lshl_add_u64 v[108:109], v[42:43], 0, v[122:123]
	v_or_b32_e32 v118, 0x4a, v34
	v_or_b32_e32 v122, 0x4b, v34
	v_ashrrev_i32_e32 v119, 31, v118
	v_ashrrev_i32_e32 v123, 31, v122
	v_lshlrev_b64 v[118:119], 10, v[118:119]
	v_mfma_f32_32x32x16_bf16 v[0:15], v[86:89], v[82:85], v[0:15]
	v_lshl_add_u64 v[82:83], v[42:43], 0, v[110:111]
	v_lshl_add_u64 v[84:85], v[42:43], 0, v[112:113]
	v_lshl_add_u64 v[86:87], v[42:43], 0, v[114:115]
	v_lshl_add_u64 v[88:89], v[42:43], 0, v[116:117]
	global_load_dword v90, v[80:81], off nt
	global_load_dword v130, v[82:83], off nt
	global_load_dword v143, v[84:85], off nt
	global_load_dword v146, v[86:87], off nt
	global_load_dword v147, v[88:89], off nt
	global_load_dword v148, v[104:105], off nt
	global_load_dword v149, v[106:107], off nt
	global_load_dword v150, v[108:109], off nt
	v_or_b32_e32 v80, 64, v34
	v_ashrrev_i32_e32 v81, 31, v80
	v_or_b32_e32 v84, 0x41, v34
	v_or_b32_e32 v88, 0x42, v34
	v_or_b32_e32 v106, 0x43, v34
	v_or_b32_e32 v110, 0x48, v34
	v_or_b32_e32 v114, 0x49, v34
	v_lshlrev_b64 v[80:81], 10, v[80:81]
	v_ashrrev_i32_e32 v85, 31, v84
	v_ashrrev_i32_e32 v89, 31, v88
	v_ashrrev_i32_e32 v107, 31, v106
	v_ashrrev_i32_e32 v111, 31, v110
	v_ashrrev_i32_e32 v115, 31, v114
	v_lshl_add_u64 v[82:83], v[40:41], 0, v[80:81]
	v_lshlrev_b64 v[84:85], 10, v[84:85]
	v_lshlrev_b64 v[88:89], 10, v[88:89]
	v_lshlrev_b64 v[106:107], 10, v[106:107]
	v_lshlrev_b64 v[110:111], 10, v[110:111]
	v_lshlrev_b64 v[114:115], 10, v[114:115]
	v_lshlrev_b64 v[122:123], 10, v[122:123]
	v_lshl_add_u64 v[86:87], v[40:41], 0, v[84:85]
	v_lshl_add_u64 v[104:105], v[40:41], 0, v[88:89]
	v_lshl_add_u64 v[108:109], v[40:41], 0, v[106:107]
	v_lshl_add_u64 v[112:113], v[40:41], 0, v[110:111]
	v_lshl_add_u64 v[116:117], v[40:41], 0, v[114:115]
	v_lshl_add_u64 v[120:121], v[40:41], 0, v[118:119]
	v_lshl_add_u64 v[144:145], v[40:41], 0, v[122:123]
	global_load_dword v151, v[82:83], off nt
	global_load_dword v152, v[86:87], off nt
	global_load_dword v153, v[104:105], off nt
	global_load_dword v182, v[108:109], off nt
	global_load_dword v183, v[112:113], off nt
	global_load_dword v184, v[116:117], off nt
	global_load_dword v185, v[120:121], off nt
	global_load_dword v186, v[144:145], off nt
	v_lshl_add_u64 v[80:81], v[42:43], 0, v[80:81]
	v_lshl_add_u64 v[82:83], v[42:43], 0, v[84:85]
	v_lshl_add_u64 v[84:85], v[42:43], 0, v[88:89]
	v_lshl_add_u64 v[86:87], v[42:43], 0, v[106:107]
	v_lshl_add_u64 v[88:89], v[42:43], 0, v[110:111]
	v_lshl_add_u64 v[104:105], v[42:43], 0, v[114:115]
	v_lshl_add_u64 v[106:107], v[42:43], 0, v[118:119]
	v_lshl_add_u64 v[108:109], v[42:43], 0, v[122:123]
	global_load_dword v187, v[80:81], off nt
	global_load_dword v188, v[82:83], off nt
	global_load_dword v189, v[84:85], off nt
	global_load_dword v190, v[86:87], off nt
	global_load_dword v191, v[88:89], off nt
	global_load_dword v192, v[104:105], off nt
	global_load_dword v193, v[106:107], off nt
	global_load_dword v194, v[108:109], off nt
	v_or_b32_e32 v80, 0x50, v34
	v_ashrrev_i32_e32 v81, 31, v80
	v_or_b32_e32 v84, 0x51, v34
	v_or_b32_e32 v88, 0x52, v34
	v_or_b32_e32 v106, 0x53, v34
	v_or_b32_e32 v110, 0x58, v34
	v_or_b32_e32 v114, 0x59, v34
	v_or_b32_e32 v118, 0x5a, v34
	v_or_b32_e32 v122, 0x5b, v34
	v_lshlrev_b64 v[80:81], 10, v[80:81]
	v_ashrrev_i32_e32 v85, 31, v84
	v_ashrrev_i32_e32 v89, 31, v88
	v_ashrrev_i32_e32 v107, 31, v106
	v_ashrrev_i32_e32 v111, 31, v110
	v_ashrrev_i32_e32 v115, 31, v114
	v_ashrrev_i32_e32 v119, 31, v118
	v_ashrrev_i32_e32 v123, 31, v122
	v_lshl_add_u64 v[82:83], v[40:41], 0, v[80:81]
	v_lshlrev_b64 v[84:85], 10, v[84:85]
	v_lshlrev_b64 v[88:89], 10, v[88:89]
	v_lshlrev_b64 v[106:107], 10, v[106:107]
	v_lshlrev_b64 v[110:111], 10, v[110:111]
	v_lshlrev_b64 v[114:115], 10, v[114:115]
	v_lshlrev_b64 v[118:119], 10, v[118:119]
	v_lshlrev_b64 v[122:123], 10, v[122:123]
	v_lshl_add_u64 v[86:87], v[40:41], 0, v[84:85]
	v_lshl_add_u64 v[104:105], v[40:41], 0, v[88:89]
	v_lshl_add_u64 v[108:109], v[40:41], 0, v[106:107]
	v_lshl_add_u64 v[112:113], v[40:41], 0, v[110:111]
	v_lshl_add_u64 v[116:117], v[40:41], 0, v[114:115]
	v_lshl_add_u64 v[120:121], v[40:41], 0, v[118:119]
	v_lshl_add_u64 v[144:145], v[40:41], 0, v[122:123]
	global_load_dword v195, v[82:83], off nt
	global_load_dword v196, v[86:87], off nt
	global_load_dword v197, v[104:105], off nt
	global_load_dword v198, v[108:109], off nt
	global_load_dword v199, v[112:113], off nt
	global_load_dword v200, v[116:117], off nt
	global_load_dword v201, v[120:121], off nt
	global_load_dword v202, v[144:145], off nt
	v_lshl_add_u64 v[80:81], v[42:43], 0, v[80:81]
	v_lshl_add_u64 v[82:83], v[42:43], 0, v[84:85]
	v_lshl_add_u64 v[84:85], v[42:43], 0, v[88:89]
	v_lshl_add_u64 v[86:87], v[42:43], 0, v[106:107]
	v_lshl_add_u64 v[88:89], v[42:43], 0, v[110:111]
	v_lshl_add_u64 v[104:105], v[42:43], 0, v[114:115]
	v_lshl_add_u64 v[106:107], v[42:43], 0, v[118:119]
	v_lshl_add_u64 v[108:109], v[42:43], 0, v[122:123]
	global_load_dword v203, v[80:81], off nt
	global_load_dword v204, v[82:83], off nt
	global_load_dword v205, v[84:85], off nt
	global_load_dword v206, v[86:87], off nt
	global_load_dword v207, v[88:89], off nt
	global_load_dword v208, v[104:105], off nt
	global_load_dword v209, v[106:107], off nt
	global_load_dword v221, v[108:109], off nt
	v_or_b32_e32 v80, 0x60, v34
	v_or_b32_e32 v122, 0x6b, v34
	v_ashrrev_i32_e32 v81, 31, v80
	v_or_b32_e32 v84, 0x61, v34
	v_or_b32_e32 v88, 0x62, v34
	v_or_b32_e32 v106, 0x63, v34
	v_or_b32_e32 v110, 0x68, v34
	v_or_b32_e32 v114, 0x69, v34
	v_or_b32_e32 v118, 0x6a, v34
	v_ashrrev_i32_e32 v123, 31, v122
	v_fma_f32 v77, v77, s18, -v181
	v_lshlrev_b64 v[80:81], 10, v[80:81]
	v_ashrrev_i32_e32 v85, 31, v84
	v_ashrrev_i32_e32 v89, 31, v88
	v_ashrrev_i32_e32 v107, 31, v106
	v_ashrrev_i32_e32 v111, 31, v110
	v_ashrrev_i32_e32 v115, 31, v114
	v_ashrrev_i32_e32 v119, 31, v118
	v_lshlrev_b64 v[122:123], 10, v[122:123]
	v_exp_f32_e32 v77, v77
	v_fma_f32 v76, v76, s18, -v181
	v_lshl_add_u64 v[82:83], v[40:41], 0, v[80:81]
	v_lshlrev_b64 v[84:85], 10, v[84:85]
	v_lshlrev_b64 v[88:89], 10, v[88:89]
	v_lshlrev_b64 v[106:107], 10, v[106:107]
	v_lshlrev_b64 v[110:111], 10, v[110:111]
	v_lshlrev_b64 v[114:115], 10, v[114:115]
	v_lshlrev_b64 v[118:119], 10, v[118:119]
	v_lshl_add_u64 v[144:145], v[40:41], 0, v[122:123]
	v_exp_f32_e32 v76, v76
	s_waitcnt vmcnt(46)
	v_cvt_pk_bf16_f32 v36, v228, v229
	v_lshl_add_u64 v[86:87], v[40:41], 0, v[84:85]
	v_lshl_add_u64 v[104:105], v[40:41], 0, v[88:89]
	v_lshl_add_u64 v[108:109], v[40:41], 0, v[106:107]
	v_lshl_add_u64 v[112:113], v[40:41], 0, v[110:111]
	v_lshl_add_u64 v[116:117], v[40:41], 0, v[114:115]
	v_lshl_add_u64 v[120:121], v[40:41], 0, v[118:119]
	global_load_dword v222, v[82:83], off nt
	global_load_dword v223, v[86:87], off nt
	global_load_dword v224, v[104:105], off nt
	global_load_dword v225, v[108:109], off nt
	global_load_dword v226, v[112:113], off nt
	global_load_dword v227, v[116:117], off nt
	global_load_dword v228, v[120:121], off nt
	s_nop 0
	global_load_dword v144, v[144:145], off nt
	v_add_f32_e32 v32, v77, v35
	v_add_f32_e32 v79, v76, v32
	v_fma_f32 v32, s17, v180, -v181
	v_lshl_add_u64 v[80:81], v[42:43], 0, v[80:81]
	v_exp_f32_e32 v78, v32
	v_cvt_pk_bf16_f32 v32, v37, v39
	s_waitcnt vmcnt(52)
	v_cvt_pk_bf16_f32 v37, v230, v231
	s_waitcnt vmcnt(50)
	v_cvt_pk_bf16_f32 v38, v232, v233
	v_lshl_add_u64 v[82:83], v[42:43], 0, v[84:85]
	v_lshl_add_u64 v[84:85], v[42:43], 0, v[88:89]
	v_lshl_add_u64 v[86:87], v[42:43], 0, v[106:107]
	v_lshl_add_u64 v[88:89], v[42:43], 0, v[110:111]
	v_lshl_add_u64 v[104:105], v[42:43], 0, v[114:115]
	v_lshl_add_u64 v[106:107], v[42:43], 0, v[118:119]
	v_lshl_add_u64 v[108:109], v[42:43], 0, v[122:123]
	global_load_dword v122, v[80:81], off nt
	global_load_dword v123, v[82:83], off nt
	global_load_dword v145, v[84:85], off nt
	global_load_dword v229, v[86:87], off nt
	global_load_dword v230, v[88:89], off nt
	global_load_dword v231, v[104:105], off nt
	global_load_dword v232, v[106:107], off nt
	global_load_dword v233, v[108:109], off nt
	v_or_b32_e32 v80, 0x70, v34
	v_or_b32_e32 v106, 0x73, v34
	v_or_b32_e32 v110, 0x78, v34
	v_or_b32_e32 v114, 0x79, v34
	v_ashrrev_i32_e32 v81, 31, v80
	v_or_b32_e32 v84, 0x71, v34
	v_or_b32_e32 v88, 0x72, v34
	v_ashrrev_i32_e32 v107, 31, v106
	v_ashrrev_i32_e32 v111, 31, v110
	v_ashrrev_i32_e32 v115, 31, v114
	v_or_b32_e32 v118, 0x7a, v34
	v_or_b32_e32 v34, 0x7b, v34
	v_lshlrev_b64 v[80:81], 10, v[80:81]
	v_ashrrev_i32_e32 v85, 31, v84
	v_ashrrev_i32_e32 v89, 31, v88
	v_lshlrev_b64 v[106:107], 10, v[106:107]
	v_lshlrev_b64 v[110:111], 10, v[110:111]
	v_lshlrev_b64 v[114:115], 10, v[114:115]
	v_ashrrev_i32_e32 v119, 31, v118
	v_ashrrev_i32_e32 v35, 31, v34
	v_lshl_add_u64 v[82:83], v[40:41], 0, v[80:81]
	v_lshlrev_b64 v[84:85], 10, v[84:85]
	v_lshlrev_b64 v[88:89], 10, v[88:89]
	v_lshl_add_u64 v[108:109], v[40:41], 0, v[106:107]
	v_lshl_add_u64 v[112:113], v[40:41], 0, v[110:111]
	v_lshl_add_u64 v[116:117], v[40:41], 0, v[114:115]
	v_lshlrev_b64 v[118:119], 10, v[118:119]
	v_lshlrev_b64 v[34:35], 10, v[34:35]
	s_waitcnt vmcnt(56)
	v_cvt_pk_bf16_f32 v39, v234, v235
	v_lshl_add_u64 v[86:87], v[40:41], 0, v[84:85]
	v_lshl_add_u64 v[104:105], v[40:41], 0, v[88:89]
	v_lshl_add_u64 v[120:121], v[40:41], 0, v[118:119]
	v_lshl_add_u64 v[40:41], v[40:41], 0, v[34:35]
	global_load_dword v234, v[82:83], off nt
	global_load_dword v235, v[86:87], off nt
	global_load_dword v236, v[104:105], off nt
	s_nop 0
	global_load_dword v108, v[108:109], off nt
	s_nop 0
	global_load_dword v109, v[112:113], off nt
	s_nop 0
	global_load_dword v112, v[116:117], off nt
	global_load_dword v113, v[120:121], off nt
	s_nop 0
	global_load_dword v116, v[40:41], off nt
	v_lshl_add_u64 v[40:41], v[42:43], 0, v[80:81]
	v_lshl_add_u64 v[80:81], v[42:43], 0, v[84:85]
	v_lshl_add_u64 v[82:83], v[42:43], 0, v[88:89]
	v_lshl_add_u64 v[84:85], v[42:43], 0, v[106:107]
	v_lshl_add_u64 v[86:87], v[42:43], 0, v[110:111]
	v_lshl_add_u64 v[88:89], v[42:43], 0, v[114:115]
	v_lshl_add_u64 v[104:105], v[42:43], 0, v[118:119]
	v_lshl_add_u64 v[34:35], v[42:43], 0, v[34:35]
	global_load_dword v40, v[40:41], off nt
	s_nop 0
	global_load_dword v41, v[80:81], off nt
	global_load_dword v42, v[82:83], off nt
	global_load_dword v43, v[84:85], off nt
	s_nop 0
	global_load_dword v80, v[86:87], off nt
	global_load_dword v81, v[88:89], off nt
	global_load_dword v82, v[104:105], off nt
	global_load_dword v83, v[34:35], off nt
	v_cvt_pk_bf16_f32 v33, v33, v64
	v_cvt_pk_bf16_f32 v34, v65, v66
	v_cvt_pk_bf16_f32 v35, v67, v69
	v_add_f32_e32 v64, v78, v79
	v_add_f32_e32 v64, v78, v64
	v_mfma_f32_32x32x16_bf16 v[16:31], v[36:39], v[32:35], v[16:31]
	s_waitcnt vmcnt(62)
	v_cvt_pk_bf16_f32 v36, v90, v130
	v_cvt_pk_bf16_f32 v37, v143, v146
	v_cvt_pk_bf16_f32 v38, v147, v148
	v_cvt_pk_bf16_f32 v39, v149, v150
	v_add_f32_e32 v64, v78, v64
	v_add_f32_e32 v64, v78, v64
	s_ashr_i32 s95, s94, 31
	v_mfma_f32_32x32x16_bf16 v[0:15], v[36:39], v[32:35], v[0:15]
	v_cvt_pk_bf16_f32 v32, v151, v152
	s_waitcnt vmcnt(60)
	v_cvt_pk_bf16_f32 v33, v153, v182
	s_waitcnt vmcnt(58)
	v_cvt_pk_bf16_f32 v34, v183, v184
	s_waitcnt vmcnt(56)
	v_cvt_pk_bf16_f32 v35, v185, v186
	v_cvt_pk_bf16_f32 v36, v44, v45
	v_cvt_pk_bf16_f32 v37, v46, v47
	v_cvt_pk_bf16_f32 v38, v49, v51
	v_cvt_pk_bf16_f32 v39, v53, v55
	v_add_f32_e32 v44, v78, v64
	v_add_f32_e32 v44, v78, v44
	v_mfma_f32_32x32x16_bf16 v[16:31], v[32:35], v[36:39], v[16:31]
	s_waitcnt vmcnt(54)
	v_cvt_pk_bf16_f32 v32, v187, v188
	s_waitcnt vmcnt(52)
	v_cvt_pk_bf16_f32 v33, v189, v190
	s_waitcnt vmcnt(50)
	v_cvt_pk_bf16_f32 v34, v191, v192
	s_waitcnt vmcnt(48)
	v_cvt_pk_bf16_f32 v35, v193, v194
	v_add_f32_e32 v44, v78, v44
	v_add_f32_e32 v44, v78, v44
	v_add_f32_e32 v44, v78, v44
	v_mfma_f32_32x32x16_bf16 v[0:15], v[32:35], v[36:39], v[0:15]
	s_waitcnt vmcnt(46)
	v_cvt_pk_bf16_f32 v32, v195, v196
	s_waitcnt vmcnt(44)
	v_cvt_pk_bf16_f32 v33, v197, v198
	s_waitcnt vmcnt(42)
	v_cvt_pk_bf16_f32 v34, v199, v200
	s_waitcnt vmcnt(40)
	v_cvt_pk_bf16_f32 v35, v201, v202
	v_cvt_pk_bf16_f32 v36, v48, v50
	v_cvt_pk_bf16_f32 v37, v52, v54
	v_cvt_pk_bf16_f32 v38, v57, v59
	v_cvt_pk_bf16_f32 v39, v61, v70
	v_add_f32_e32 v44, v78, v44
	v_add_f32_e32 v44, v78, v44
	v_mfma_f32_32x32x16_bf16 v[16:31], v[32:35], v[36:39], v[16:31]
	s_waitcnt vmcnt(38)
	v_cvt_pk_bf16_f32 v32, v203, v204
	s_waitcnt vmcnt(36)
	v_cvt_pk_bf16_f32 v33, v205, v206
	s_waitcnt vmcnt(34)
	v_cvt_pk_bf16_f32 v34, v207, v208
	s_waitcnt vmcnt(32)
	v_cvt_pk_bf16_f32 v35, v209, v221
	v_add_f32_e32 v183, v78, v44
	ds_bpermute_b32 v184, v68, v183
	s_lshl_b64 s[24:25], s[94:95], 9
	v_mfma_f32_32x32x16_bf16 v[0:15], v[32:35], v[36:39], v[0:15]
	s_waitcnt vmcnt(30)
	v_cvt_pk_bf16_f32 v32, v222, v223
	s_waitcnt vmcnt(28)
	v_cvt_pk_bf16_f32 v33, v224, v225
	s_waitcnt vmcnt(26)
	v_cvt_pk_bf16_f32 v34, v226, v227
	s_waitcnt vmcnt(24)
	v_cvt_pk_bf16_f32 v35, v228, v144
	v_cvt_pk_bf16_f32 v36, v56, v58
	v_cvt_pk_bf16_f32 v37, v60, v63
	v_cvt_pk_bf16_f32 v38, v71, v73
	v_cvt_pk_bf16_f32 v39, v74, v75
	s_add_u32 s13, s56, s24
	s_addc_u32 s15, s57, s25
	v_mfma_f32_32x32x16_bf16 v[16:31], v[32:35], v[36:39], v[16:31]
	s_waitcnt vmcnt(22)
	v_cvt_pk_bf16_f32 v32, v122, v123
	s_waitcnt vmcnt(20)
	v_cvt_pk_bf16_f32 v33, v145, v229
	s_waitcnt vmcnt(18)
	v_cvt_pk_bf16_f32 v34, v230, v231
	s_waitcnt vmcnt(16)
	v_cvt_pk_bf16_f32 v35, v232, v233
	s_lshl_b32 s14, s14, 1
	s_add_u32 s94, s13, s14
	s_addc_u32 s95, s15, 0
	v_mfma_f32_32x32x16_bf16 v[0:15], v[32:35], v[36:39], v[0:15]
	s_waitcnt vmcnt(14)
	v_cvt_pk_bf16_f32 v32, v234, v235
	s_waitcnt vmcnt(12)
	v_cvt_pk_bf16_f32 v33, v236, v108
	s_waitcnt vmcnt(10)
	v_cvt_pk_bf16_f32 v34, v109, v112
	s_waitcnt vmcnt(8)
	v_cvt_pk_bf16_f32 v35, v113, v116
	v_cvt_pk_bf16_f32 v36, v62, v72
	v_cvt_pk_bf16_f32 v37, v93, v94
	v_cvt_pk_bf16_f32 v38, v95, v98
	v_cvt_pk_bf16_f32 v39, v99, v102
	v_readlane_b32 s69, v254, 19
	v_readlane_b32 s70, v254, 20
	v_mfma_f32_32x32x16_bf16 v[16:31], v[32:35], v[36:39], v[16:31]
	s_waitcnt vmcnt(6)
	v_cvt_pk_bf16_f32 v32, v40, v41
	s_waitcnt vmcnt(4)
	v_cvt_pk_bf16_f32 v33, v42, v43
	s_waitcnt vmcnt(2)
	v_cvt_pk_bf16_f32 v34, v80, v81
	s_waitcnt vmcnt(0)
	v_cvt_pk_bf16_f32 v35, v82, v83
	v_readlane_b32 s71, v254, 21
	s_nop 0
	v_mfma_f32_32x32x16_bf16 v[0:15], v[32:35], v[36:39], v[0:15]
	v_mov_b32_e32 v34, 0
	v_mov_b32_e32 v32, 0
	v_mov_b32_e32 v33, 0
	s_and_saveexec_b64 vcc, s[4:5]
	s_cbranch_execz .LBB0_742
	v_lshlrev_b32_e32 v33, 1, v136
	global_load_ushort v32, v33, s[94:95]
	global_load_ushort v35, v33, s[94:95] offset:512
	s_waitcnt vmcnt(0)
	v_lshl_or_b32 v32, v35, 16, v32
	global_load_ushort v35, v33, s[94:95] offset:1024
	s_nop 0
	global_load_ushort v33, v33, s[94:95] offset:1536
	s_waitcnt vmcnt(0)
	v_lshl_or_b32 v33, v33, 16, v35
